# norm phase: all loads of an iteration issued back to back, one counted wait (was vmcnt(0) after each D load)
# speedup vs baseline: 1.0050x; 1.0050x over previous
; #define BIDX (opaque_bid() * 2 + HALF_)
; __device__ __forceinline__ void phase_norm(const Params& p, int mode, const u16* D, const float* gD, float scale,
;                            const float* gH, bool writeH) {
;     ...
;   for (int it = BIDX; it < T_TOK / 8; it += VGRID) {
;     const int row0 = it * 8 + wave * 2;
;     float4 xv[2][4], dv[2][4], g1[4], g2[4];
; #pragma unroll
;     for (int r = 0; r < 2; ++r)
; #pragma unroll
;       for (int i = 0; i < 4; ++i) {
;         xv[r][i] = *(const float4*)(xsrc + (size_t)(row0 + r) * DM + i * 256 + lane * 4);
;         if (mode == 1) {
;           const uint2 w = *(const uint2*)(D + (size_t)(row0 + r) * DM + i * 256 + lane * 4);
;           dv[r][i] = make_float4(__uint_as_float(w.x << 16), __uint_as_float(w.x & 0xffff0000u),
;                                  __uint_as_float(w.y << 16), __uint_as_float(w.y & 0xffff0000u));
;         } else {
;           dv[r][i] = make_float4(0.f, 0.f, 0.f, 0.f);
;         }
;       }
; #pragma unroll
;     for (int i = 0; i < 4; ++i) {
;       g1[i] = (mode == 1) ? *(const float4*)(gD + i * 256 + lane * 4) : make_float4(0.f, 0.f, 0.f, 0.f);
;       g2[i] = writeH ? *(const float4*)(gH + i * 256 + lane * 4) : make_float4(0.f, 0.f, 0.f, 0.f);
;     }
;     __builtin_amdgcn_sched_barrier(0);
;     if (mode == 1) {
;       float ss0 = 0.f, ss1 = 0.f;
; #pragma unroll
;       for (int i = 0; i < 4; ++i) {
;         ss0 += dv[0][i].x * dv[0][i].x + dv[0][i].y * dv[0][i].y + dv[0][i].z * dv[0][i].z + dv[0][i].w * dv[0][i].w;
;         ss1 += dv[1][i].x * dv[1][i].x + dv[1][i].y * dv[1][i].y + dv[1][i].z * dv[1][i].z + dv[1][i].w * dv[1][i].w;
.LBB0_495:
	v_ashrrev_i32_e32 v79, 31, v78
	v_add_u32_e32 v22, 1, v78
	v_lshlrev_b64 v[84:85], 12, v[78:79]
	v_lshlrev_b64 v[80:81], 11, v[78:79]
	v_ashrrev_i32_e32 v23, 31, v22
	v_cndmask_b32_e64 v0, 0, 1, s[24:25]
	v_lshlrev_b64 v[86:87], 12, v[22:23]
	v_lshlrev_b64 v[82:83], 11, v[22:23]
	v_cmp_ne_u32_e64 s[40:41], 1, v0
	v_cndmask_b32_e64 v0, 0, 1, s[20:21]
	v_lshl_add_u64 v[122:123], v[66:67], 0, v[84:85]
	v_lshl_add_u64 v[124:125], v[68:69], 0, v[80:81]
	v_cmp_ne_u32_e64 s[38:39], 1, v0
	v_lshl_add_u64 v[126:127], v[66:67], 0, v[86:87]
	v_lshl_add_u64 v[128:129], v[68:69], 0, v[82:83]
	s_and_b64 vcc, exec, s[40:41]
	s_cbranch_vccnz .Lnorm_nog1
	global_load_dwordx4 v[50:53], v[70:71], off
	global_load_dwordx4 v[54:57], v[70:71], off offset:1024
	global_load_dwordx4 v[58:61], v[70:71], off offset:2048
	global_load_dwordx4 v[62:65], v[70:71], off offset:3072
.Lnorm_nog1:
	s_and_b64 vcc, exec, s[38:39]
	s_cbranch_vccnz .Lnorm_nog2
	global_load_dwordx4 v[34:37], v[72:73], off
	global_load_dwordx4 v[38:41], v[72:73], off offset:1024
	global_load_dwordx4 v[42:45], v[72:73], off offset:2048
	global_load_dwordx4 v[46:49], v[72:73], off offset:3072
.Lnorm_nog2:
	s_and_b64 vcc, exec, s[40:41]
	s_cbranch_vccnz .Lnorm_nod
	global_load_dwordx2 v[92:93], v[124:125], off
	global_load_dwordx2 v[94:95], v[124:125], off offset:512
	global_load_dwordx2 v[100:101], v[124:125], off offset:1024
	global_load_dwordx2 v[102:103], v[124:125], off offset:1536
	global_load_dwordx2 v[108:109], v[128:129], off
	global_load_dwordx2 v[110:111], v[128:129], off offset:512
	global_load_dwordx2 v[116:117], v[128:129], off offset:1024
	global_load_dwordx2 v[118:119], v[128:129], off offset:1536
.Lnorm_nod:
	global_load_dwordx4 v[2:5], v[122:123], off
	global_load_dwordx4 v[6:9], v[122:123], off offset:1024
	global_load_dwordx4 v[10:13], v[122:123], off offset:2048
	global_load_dwordx4 v[14:17], v[122:123], off offset:3072
	global_load_dwordx4 v[18:21], v[126:127], off
	global_load_dwordx4 v[22:25], v[126:127], off offset:1024
	global_load_dwordx4 v[26:29], v[126:127], off offset:2048
	global_load_dwordx4 v[30:33], v[126:127], off offset:3072
.LBB0_527:
	s_and_b64 vcc, exec, s[24:25]
	s_cbranch_vccz .LBB0_529
	s_waitcnt vmcnt(8)
	v_lshlrev_b32_e32 v90, 16, v93
	v_and_b32_e32 v91, 0xffff0000, v93
	v_and_b32_e32 v93, 0xffff0000, v92
	v_lshlrev_b32_e32 v92, 16, v92
	v_lshlrev_b32_e32 v88, 16, v95
	v_and_b32_e32 v89, 0xffff0000, v95
	v_and_b32_e32 v95, 0xffff0000, v94
	v_lshlrev_b32_e32 v94, 16, v94
	v_lshlrev_b32_e32 v98, 16, v101
	v_and_b32_e32 v99, 0xffff0000, v101
	v_and_b32_e32 v101, 0xffff0000, v100
	v_lshlrev_b32_e32 v100, 16, v100
	v_lshlrev_b32_e32 v96, 16, v103
	v_and_b32_e32 v97, 0xffff0000, v103
	v_and_b32_e32 v103, 0xffff0000, v102
	v_lshlrev_b32_e32 v102, 16, v102
	v_lshlrev_b32_e32 v106, 16, v109
	v_and_b32_e32 v107, 0xffff0000, v109
	v_and_b32_e32 v109, 0xffff0000, v108
	v_lshlrev_b32_e32 v108, 16, v108
	v_lshlrev_b32_e32 v104, 16, v111
	v_and_b32_e32 v105, 0xffff0000, v111
	v_and_b32_e32 v111, 0xffff0000, v110
	v_lshlrev_b32_e32 v110, 16, v110
	v_lshlrev_b32_e32 v114, 16, v117
	v_and_b32_e32 v115, 0xffff0000, v117
	v_and_b32_e32 v117, 0xffff0000, v116
	v_lshlrev_b32_e32 v116, 16, v116
	v_lshlrev_b32_e32 v112, 16, v119
	v_and_b32_e32 v113, 0xffff0000, v119
	v_and_b32_e32 v119, 0xffff0000, v118
	v_lshlrev_b32_e32 v118, 16, v118
	v_mov_b32_e32 v122, v92
	v_mov_b32_e32 v123, v94
	v_pk_mul_f32 v[122:123], v[122:123], v[122:123]
	v_mov_b32_e32 v124, v93
	v_mov_b32_e32 v125, v95
	v_pk_fma_f32 v[122:123], v[124:125], v[124:125], v[122:123]
	v_mov_b32_e32 v124, v90
	v_mov_b32_e32 v125, v88
	v_pk_fma_f32 v[122:123], v[124:125], v[124:125], v[122:123]
	v_mov_b32_e32 v124, v91
	v_mov_b32_e32 v125, v89
	v_pk_fma_f32 v[122:123], v[124:125], v[124:125], v[122:123]
	v_mov_b32_e32 v124, v108
	v_mov_b32_e32 v125, v110
	v_pk_mul_f32 v[124:125], v[124:125], v[124:125]
	v_mov_b32_e32 v126, v109
	v_mov_b32_e32 v127, v111
	v_pk_fma_f32 v[124:125], v[126:127], v[126:127], v[124:125]
	v_mov_b32_e32 v126, v106
	v_mov_b32_e32 v127, v104
	v_pk_fma_f32 v[124:125], v[126:127], v[126:127], v[124:125]
	v_mov_b32_e32 v126, v107
	v_mov_b32_e32 v127, v105
	v_pk_fma_f32 v[124:125], v[126:127], v[126:127], v[124:125]
	v_mov_b32_e32 v126, v100
	v_mov_b32_e32 v127, v102
	v_pk_mul_f32 v[126:127], v[126:127], v[126:127]
	v_mov_b32_e32 v128, v101
	v_mov_b32_e32 v129, v103
	v_pk_fma_f32 v[126:127], v[128:129], v[128:129], v[126:127]
	v_mov_b32_e32 v128, v98
	v_mov_b32_e32 v129, v96
	v_pk_fma_f32 v[126:127], v[128:129], v[128:129], v[126:127]
	v_mov_b32_e32 v128, v99
	v_mov_b32_e32 v129, v97
	v_pk_fma_f32 v[126:127], v[128:129], v[128:129], v[126:127]
	v_mov_b32_e32 v128, v116
	v_mov_b32_e32 v129, v118
	v_pk_mul_f32 v[128:129], v[128:129], v[128:129]
	v_mov_b32_e32 v130, v117
	v_mov_b32_e32 v131, v119
	v_pk_fma_f32 v[128:129], v[130:131], v[130:131], v[128:129]
	v_mov_b32_e32 v130, v114
	v_mov_b32_e32 v131, v112
	v_pk_fma_f32 v[128:129], v[130:131], v[130:131], v[128:129]
	v_mov_b32_e32 v130, v115
	v_mov_b32_e32 v131, v113
	v_and_b32_e32 v0, 64, v202
	v_pk_fma_f32 v[128:129], v[130:131], v[130:131], v[128:129]
	v_add_u32_e32 v0, 64, v0
	v_xor_b32_e32 v79, 32, v202
	v_mov_b32_e32 v130, v124
	v_mov_b32_e32 v131, v122
	v_mov_b32_e32 v122, v125
	v_cmp_lt_i32_e32 vcc, v79, v0
	v_pk_add_f32 v[122:123], v[130:131], v[122:123]
	v_mov_b32_e32 v124, v128
	v_mov_b32_e32 v125, v126
	v_cndmask_b32_e32 v79, v202, v79, vcc
	v_pk_add_f32 v[122:123], v[122:123], v[124:125]
	v_mov_b32_e32 v126, v129
	v_lshlrev_b32_e32 v79, 2, v79
	v_pk_add_f32 v[122:123], v[122:123], v[126:127]
	ds_bpermute_b32 v125, v79, v123
	ds_bpermute_b32 v124, v79, v122
	v_xor_b32_e32 v79, 16, v202
	v_cmp_lt_i32_e32 vcc, v79, v0
	s_waitcnt lgkmcnt(0)
; __device__ __forceinline__ void phase_norm(const Params& p, int mode, const u16* D, const float* gD, float scale,
;                            const float* gH, bool writeH) {
;     ...
;       for (int o = 32; o; o >>= 1) { ss0 += __shfl_xor(ss0, o); ss1 += __shfl_xor(ss1, o); }
;       const float r0 = rsqrtf(ss0 * (1.0f / DM) + EPSN) * scale;
;       const float r1 = rsqrtf(ss1 * (1.0f / DM) + EPSN) * scale;
; #pragma unroll
;       for (int i = 0; i < 4; ++i) {
;         xv[0][i].x += dv[0][i].x * r0 * g1[i].x; xv[0][i].y += dv[0][i].y * r0 * g1[i].y;
;         xv[0][i].z += dv[0][i].z * r0 * g1[i].z; xv[0][i].w += dv[0][i].w * r0 * g1[i].w;
;         xv[1][i].x += dv[1][i].x * r1 * g1[i].x; xv[1][i].y += dv[1][i].y * r1 * g1[i].y;
;         xv[1][i].z += dv[1][i].z * r1 * g1[i].z; xv[1][i].w += dv[1][i].w * r1 * g1[i].w;
;       }
	v_pk_add_f32 v[122:123], v[122:123], v[124:125]
	v_cndmask_b32_e32 v79, v202, v79, vcc
	v_lshlrev_b32_e32 v79, 2, v79
	ds_bpermute_b32 v125, v79, v123
	ds_bpermute_b32 v124, v79, v122
	v_xor_b32_e32 v79, 8, v202
	v_cmp_lt_i32_e32 vcc, v79, v0
	s_waitcnt lgkmcnt(0)
	v_pk_add_f32 v[122:123], v[122:123], v[124:125]
	v_cndmask_b32_e32 v79, v202, v79, vcc
	v_lshlrev_b32_e32 v79, 2, v79
	ds_bpermute_b32 v125, v79, v123
	ds_bpermute_b32 v124, v79, v122
	v_xor_b32_e32 v79, 4, v202
	v_cmp_lt_i32_e32 vcc, v79, v0
	s_waitcnt lgkmcnt(0)
	v_pk_add_f32 v[122:123], v[122:123], v[124:125]
	v_cndmask_b32_e32 v79, v202, v79, vcc
	v_lshlrev_b32_e32 v79, 2, v79
	ds_bpermute_b32 v125, v79, v123
	ds_bpermute_b32 v124, v79, v122
	v_xor_b32_e32 v79, 2, v202
	v_cmp_lt_i32_e32 vcc, v79, v0
	s_waitcnt lgkmcnt(0)
	v_pk_add_f32 v[122:123], v[122:123], v[124:125]
	v_cndmask_b32_e32 v79, v202, v79, vcc
	v_lshlrev_b32_e32 v79, 2, v79
	ds_bpermute_b32 v125, v79, v123
	ds_bpermute_b32 v124, v79, v122
	v_xor_b32_e32 v79, 1, v202
	v_cmp_lt_i32_e32 vcc, v79, v0
	s_waitcnt lgkmcnt(0)
	v_pk_add_f32 v[122:123], v[122:123], v[124:125]
	v_cndmask_b32_e32 v0, v202, v79, vcc
	v_lshlrev_b32_e32 v0, 2, v0
	ds_bpermute_b32 v125, v0, v123
	ds_bpermute_b32 v124, v0, v122
	s_waitcnt lgkmcnt(0)
	v_pk_add_f32 v[122:123], v[122:123], v[124:125]
	s_nop 0
	v_pk_fma_f32 v[122:123], v[122:123], s[22:23], v[174:175] op_sel_hi:[1,0,0]
	s_nop 0
	v_mul_f32_e32 v0, 0x4b800000, v123
	v_cmp_gt_f32_e32 vcc, s56, v123
	v_mul_f32_e32 v79, 0x4b800000, v122
	v_cmp_gt_f32_e64 s[0:1], s56, v122
	v_cndmask_b32_e32 v0, v123, v0, vcc
	v_rsq_f32_e32 v0, v0
	v_cndmask_b32_e64 v79, v122, v79, s[0:1]
	v_rsq_f32_e32 v79, v79
	v_mul_f32_e32 v121, 0x45800000, v0
	v_cndmask_b32_e32 v0, v0, v121, vcc
	v_mul_f32_e32 v121, 0x45800000, v79
	v_mul_f32_e32 v0, v120, v0
	v_cndmask_b32_e64 v79, v79, v121, s[0:1]
	v_mul_f32_e32 v122, v120, v79
	v_pk_mul_f32 v[90:91], v[90:91], v[0:1] op_sel_hi:[1,0]
	v_pk_mul_f32 v[92:93], v[92:93], v[0:1] op_sel_hi:[1,0]
	s_waitcnt vmcnt(0)
	v_pk_fma_f32 v[4:5], v[52:53], v[90:91], v[4:5]
	v_pk_mul_f32 v[90:91], v[108:109], v[122:123] op_sel_hi:[1,0]
	v_pk_fma_f32 v[2:3], v[50:51], v[92:93], v[2:3]
	v_pk_fma_f32 v[18:19], v[50:51], v[90:91], v[18:19]
	v_pk_mul_f32 v[50:51], v[106:107], v[122:123] op_sel_hi:[1,0]
	s_nop 0
	v_pk_fma_f32 v[20:21], v[52:53], v[50:51], v[20:21]
	v_pk_mul_f32 v[50:51], v[94:95], v[0:1] op_sel_hi:[1,0]
	s_nop 0
	v_pk_fma_f32 v[6:7], v[54:55], v[50:51], v[6:7]
	v_pk_mul_f32 v[50:51], v[88:89], v[0:1] op_sel_hi:[1,0]
	s_nop 0
	v_pk_fma_f32 v[8:9], v[56:57], v[50:51], v[8:9]
	v_pk_mul_f32 v[50:51], v[110:111], v[122:123] op_sel_hi:[1,0]
	s_nop 0
	v_pk_fma_f32 v[22:23], v[54:55], v[50:51], v[22:23]
	v_pk_mul_f32 v[50:51], v[104:105], v[122:123] op_sel_hi:[1,0]
	s_nop 0
	v_pk_fma_f32 v[24:25], v[56:57], v[50:51], v[24:25]
	v_pk_mul_f32 v[50:51], v[100:101], v[0:1] op_sel_hi:[1,0]
	s_nop 0
	v_pk_fma_f32 v[10:11], v[58:59], v[50:51], v[10:11]
	v_pk_mul_f32 v[50:51], v[98:99], v[0:1] op_sel_hi:[1,0]
	s_nop 0
	v_pk_fma_f32 v[12:13], v[60:61], v[50:51], v[12:13]
	v_pk_mul_f32 v[50:51], v[116:117], v[122:123] op_sel_hi:[1,0]
	s_nop 0
	v_pk_fma_f32 v[26:27], v[58:59], v[50:51], v[26:27]
	v_pk_mul_f32 v[50:51], v[114:115], v[122:123] op_sel_hi:[1,0]
	s_nop 0
	v_pk_fma_f32 v[28:29], v[60:61], v[50:51], v[28:29]
	v_pk_mul_f32 v[50:51], v[102:103], v[0:1] op_sel_hi:[1,0]
	s_nop 0
	v_pk_fma_f32 v[14:15], v[62:63], v[50:51], v[14:15]
	v_pk_mul_f32 v[50:51], v[96:97], v[0:1] op_sel_hi:[1,0]
	s_nop 0
	v_pk_fma_f32 v[16:17], v[64:65], v[50:51], v[16:17]
	v_pk_mul_f32 v[50:51], v[118:119], v[122:123] op_sel_hi:[1,0]
	s_nop 0
	v_pk_fma_f32 v[30:31], v[62:63], v[50:51], v[30:31]
	v_pk_mul_f32 v[50:51], v[112:113], v[122:123] op_sel_hi:[1,0]
	s_nop 0
	v_pk_fma_f32 v[32:33], v[64:65], v[50:51], v[32:33]
